# write-through (sc1) stores for the MLP-up hidden tensor only
# speedup vs baseline: 1.0142x; 1.0142x over previous
.LBB0_702:
	v_lshl_add_u32 v146, s6, 8, v148
	v_ashrrev_i32_e32 v147, 31, v146
	v_lshlrev_b64 v[144:145], 6, v[146:147]
	v_lshl_add_u64 v[144:145], s[10:11], 0, v[144:145]
	global_load_dwordx4 v[156:159], v[144:145], off
	global_load_dwordx4 v[160:163], v[144:145], off offset:16
	global_load_dwordx4 v[164:167], v[144:145], off offset:32
	global_load_dwordx4 v[168:171], v[144:145], off offset:48
	v_lshlrev_b64 v[174:175], 13, v[146:147]
	v_lshl_or_b32 v144, s7, 8, v150
	v_ashrrev_i32_e32 v145, 31, v144
	v_or_b32_e32 v172, 16, v146
	v_lshl_add_u64 v[144:145], v[144:145], 1, s[12:13]
	v_ashrrev_i32_e32 v173, 31, v172
	s_waitcnt vmcnt(0)
	v_pk_add_f32 v[158:159], v[158:159], v[162:163]
	v_pk_add_f32 v[156:157], v[156:157], v[160:161]
	v_pk_add_f32 v[160:161], v[166:167], v[170:171]
	v_pk_add_f32 v[162:163], v[164:165], v[168:169]
	v_pk_add_f32 v[158:159], v[158:159], v[160:161]
	v_pk_add_f32 v[156:157], v[156:157], v[162:163]
	s_nop 0
	v_pk_mov_b32 v[160:161], v[156:157], v[158:159] op_sel:[1,0]
	v_mov_b32_e32 v157, v159
	v_pk_add_f32 v[156:157], v[160:161], v[156:157]
	v_lshlrev_b64 v[158:159], 6, v[172:173]
	v_add_f32_e32 v147, v156, v157
	v_fmamk_f32 v147, v147, 0x3a800000, v154
	v_mul_f32_e32 v155, 0x4b800000, v147
	v_cmp_gt_f32_e32 vcc, s48, v147
	v_lshl_add_u64 v[156:157], v[144:145], 0, v[174:175]
	v_lshl_add_u64 v[158:159], s[10:11], 0, v[158:159]
	v_cndmask_b32_e32 v147, v147, v155, vcc
	v_rsq_f32_e32 v147, v147
	s_nop 0
	v_mul_f32_e32 v155, 0x45800000, v147
	v_cndmask_b32_e32 v160, v147, v155, vcc
	v_pk_mul_f32 v[126:127], v[126:127], v[160:161] op_sel_hi:[1,0]
	v_pk_mul_f32 v[124:125], v[124:125], v[160:161] op_sel_hi:[1,0]
	v_pk_mul_f32 v[122:123], v[122:123], v[160:161] op_sel_hi:[1,0]
	v_pk_mul_f32 v[120:121], v[120:121], v[160:161] op_sel_hi:[1,0]
	v_pk_mul_f32 v[114:115], v[114:115], v[160:161] op_sel_hi:[1,0]
	v_pk_mul_f32 v[112:113], v[112:113], v[160:161] op_sel_hi:[1,0]
	v_pk_mul_f32 v[118:119], v[118:119], v[160:161] op_sel_hi:[1,0]
	v_pk_mul_f32 v[116:117], v[116:117], v[160:161] op_sel_hi:[1,0]
	v_max_f32_e32 v124, 0, v124
	v_max_f32_e32 v120, 0, v120
	v_max_f32_e32 v125, 0, v125
	v_max_f32_e32 v121, 0, v121
	v_max_f32_e32 v126, 0, v126
	v_max_f32_e32 v122, 0, v122
	v_max_f32_e32 v127, 0, v127
	v_max_f32_e32 v123, 0, v123
	v_max_f32_e32 v112, 0, v112
	v_max_f32_e32 v113, 0, v113
	v_max_f32_e32 v114, 0, v114
	v_max_f32_e32 v115, 0, v115
	v_max_f32_e32 v116, 0, v116
	v_max_f32_e32 v117, 0, v117
	v_max_f32_e32 v118, 0, v118
	v_max_f32_e32 v119, 0, v119
	v_mul_f32_e32 v124, v124, v124
	v_mul_f32_e32 v120, v120, v120
	v_mul_f32_e32 v125, v125, v125
	v_mul_f32_e32 v121, v121, v121
	v_mul_f32_e32 v126, v126, v126
	v_mul_f32_e32 v122, v122, v122
	v_mul_f32_e32 v127, v127, v127
	v_mul_f32_e32 v123, v123, v123
	v_mul_f32_e32 v147, v112, v112
	v_mul_f32_e32 v155, v113, v113
	v_mul_f32_e32 v160, v114, v114
	v_mul_f32_e32 v161, v115, v115
	v_cvt_pk_bf16_f32 v112, v124, v125
	v_cvt_pk_bf16_f32 v113, v126, v127
	v_cvt_pk_bf16_f32 v114, v120, v121
	v_cvt_pk_bf16_f32 v115, v122, v123
	v_mul_f32_e32 v116, v116, v116
	v_mul_f32_e32 v117, v117, v117
	v_mul_f32_e32 v118, v118, v118
	v_mul_f32_e32 v119, v119, v119
	global_store_dwordx4 v[156:157], v[112:115], off sc1
	s_nop 1
	v_cvt_pk_bf16_f32 v112, v116, v117
	v_cvt_pk_bf16_f32 v113, v118, v119
	v_cvt_pk_bf16_f32 v114, v147, v155
	v_cvt_pk_bf16_f32 v115, v160, v161
	global_store_dwordx4 v[156:157], v[112:115], off offset:256 sc1
	global_load_dwordx4 v[112:115], v[158:159], off
	s_nop 0
	global_load_dwordx4 v[116:119], v[158:159], off offset:16
	global_load_dwordx4 v[120:123], v[158:159], off offset:32
	global_load_dwordx4 v[124:127], v[158:159], off offset:48
	v_or_b32_e32 v156, 32, v146
	v_ashrrev_i32_e32 v157, 31, v156
	v_lshlrev_b64 v[158:159], 13, v[172:173]
	s_waitcnt vmcnt(2)
	v_pk_add_f32 v[114:115], v[114:115], v[118:119]
	v_pk_add_f32 v[112:113], v[112:113], v[116:117]
	s_waitcnt vmcnt(0)
	v_pk_add_f32 v[116:117], v[122:123], v[126:127]
	v_pk_add_f32 v[118:119], v[120:121], v[124:125]
	v_pk_add_f32 v[114:115], v[114:115], v[116:117]
	v_pk_add_f32 v[112:113], v[112:113], v[118:119]
	s_nop 0
	v_pk_mov_b32 v[116:117], v[112:113], v[114:115] op_sel:[1,0]
	v_mov_b32_e32 v113, v115
	v_pk_add_f32 v[112:113], v[116:117], v[112:113]
	v_lshl_add_u64 v[114:115], v[144:145], 0, v[158:159]
	v_add_f32_e32 v112, v112, v113
	v_fmamk_f32 v112, v112, 0x3a800000, v154
	v_mul_f32_e32 v113, 0x4b800000, v112
	v_cmp_gt_f32_e32 vcc, s48, v112
	s_nop 1
	v_cndmask_b32_e32 v112, v112, v113, vcc
	v_rsq_f32_e32 v116, v112
	v_lshlrev_b64 v[112:113], 6, v[156:157]
	v_lshl_add_u64 v[112:113], s[10:11], 0, v[112:113]
	v_mul_f32_e32 v117, 0x45800000, v116
	v_cndmask_b32_e32 v116, v116, v117, vcc
	v_pk_mul_f32 v[110:111], v[110:111], v[116:117] op_sel_hi:[1,0]
	v_pk_mul_f32 v[108:109], v[108:109], v[116:117] op_sel_hi:[1,0]
	v_pk_mul_f32 v[106:107], v[106:107], v[116:117] op_sel_hi:[1,0]
	v_pk_mul_f32 v[104:105], v[104:105], v[116:117] op_sel_hi:[1,0]
	v_pk_mul_f32 v[98:99], v[98:99], v[116:117] op_sel_hi:[1,0]
	v_pk_mul_f32 v[96:97], v[96:97], v[116:117] op_sel_hi:[1,0]
	v_pk_mul_f32 v[102:103], v[102:103], v[116:117] op_sel_hi:[1,0]
	v_pk_mul_f32 v[100:101], v[100:101], v[116:117] op_sel_hi:[1,0]
	v_max_f32_e32 v108, 0, v108
	v_max_f32_e32 v104, 0, v104
	v_max_f32_e32 v109, 0, v109
	v_max_f32_e32 v105, 0, v105
	v_max_f32_e32 v110, 0, v110
	v_max_f32_e32 v106, 0, v106
	v_max_f32_e32 v111, 0, v111
	v_max_f32_e32 v107, 0, v107
	v_max_f32_e32 v96, 0, v96
	v_max_f32_e32 v97, 0, v97
	v_max_f32_e32 v98, 0, v98
	v_max_f32_e32 v99, 0, v99
	v_max_f32_e32 v100, 0, v100
	v_max_f32_e32 v101, 0, v101
	v_max_f32_e32 v102, 0, v102
	v_max_f32_e32 v103, 0, v103
	v_mul_f32_e32 v108, v108, v108
	v_mul_f32_e32 v104, v104, v104
	v_mul_f32_e32 v109, v109, v109
	v_mul_f32_e32 v105, v105, v105
	v_mul_f32_e32 v110, v110, v110
	v_mul_f32_e32 v106, v106, v106
	v_mul_f32_e32 v111, v111, v111
	v_mul_f32_e32 v107, v107, v107
	v_mul_f32_e32 v116, v96, v96
	v_mul_f32_e32 v117, v97, v97
	v_mul_f32_e32 v118, v98, v98
	v_mul_f32_e32 v119, v99, v99
	v_cvt_pk_bf16_f32 v96, v108, v109
	v_cvt_pk_bf16_f32 v97, v110, v111
	v_cvt_pk_bf16_f32 v98, v104, v105
	v_cvt_pk_bf16_f32 v99, v106, v107
	v_mul_f32_e32 v100, v100, v100
	v_mul_f32_e32 v101, v101, v101
	v_mul_f32_e32 v102, v102, v102
	v_mul_f32_e32 v103, v103, v103
	global_store_dwordx4 v[114:115], v[96:99], off sc1
	s_nop 1
	v_cvt_pk_bf16_f32 v96, v100, v101
	v_cvt_pk_bf16_f32 v97, v102, v103
	v_cvt_pk_bf16_f32 v98, v116, v117
	v_cvt_pk_bf16_f32 v99, v118, v119
	global_store_dwordx4 v[114:115], v[96:99], off offset:256 sc1
	global_load_dwordx4 v[96:99], v[112:113], off
	s_nop 0
	global_load_dwordx4 v[100:103], v[112:113], off offset:16
	global_load_dwordx4 v[104:107], v[112:113], off offset:32
	global_load_dwordx4 v[108:111], v[112:113], off offset:48
	v_or_b32_e32 v112, 48, v146
	v_ashrrev_i32_e32 v113, 31, v112
	v_lshlrev_b64 v[114:115], 13, v[156:157]
	s_waitcnt vmcnt(2)
	v_pk_add_f32 v[98:99], v[98:99], v[102:103]
	v_pk_add_f32 v[96:97], v[96:97], v[100:101]
	s_waitcnt vmcnt(0)
	v_pk_add_f32 v[100:101], v[106:107], v[110:111]
	v_pk_add_f32 v[102:103], v[104:105], v[108:109]
	v_pk_add_f32 v[98:99], v[98:99], v[100:101]
	v_pk_add_f32 v[96:97], v[96:97], v[102:103]
	s_nop 0
	v_pk_mov_b32 v[100:101], v[96:97], v[98:99] op_sel:[1,0]
	v_mov_b32_e32 v97, v99
	v_pk_add_f32 v[96:97], v[100:101], v[96:97]
	v_lshl_add_u64 v[98:99], v[144:145], 0, v[114:115]
	v_add_f32_e32 v96, v96, v97
	v_fmamk_f32 v96, v96, 0x3a800000, v154
	v_mul_f32_e32 v97, 0x4b800000, v96
	v_cmp_gt_f32_e32 vcc, s48, v96
	s_nop 1
	v_cndmask_b32_e32 v96, v96, v97, vcc
	v_rsq_f32_e32 v100, v96
	v_lshlrev_b64 v[96:97], 6, v[112:113]
	v_lshl_add_u64 v[96:97], s[10:11], 0, v[96:97]
	v_mul_f32_e32 v101, 0x45800000, v100
	v_cndmask_b32_e32 v100, v100, v101, vcc
	v_pk_mul_f32 v[94:95], v[94:95], v[100:101] op_sel_hi:[1,0]
	v_pk_mul_f32 v[92:93], v[92:93], v[100:101] op_sel_hi:[1,0]
	v_pk_mul_f32 v[90:91], v[90:91], v[100:101] op_sel_hi:[1,0]
	v_pk_mul_f32 v[88:89], v[88:89], v[100:101] op_sel_hi:[1,0]
	v_pk_mul_f32 v[82:83], v[82:83], v[100:101] op_sel_hi:[1,0]
	v_pk_mul_f32 v[80:81], v[80:81], v[100:101] op_sel_hi:[1,0]
	v_pk_mul_f32 v[86:87], v[86:87], v[100:101] op_sel_hi:[1,0]
	v_pk_mul_f32 v[84:85], v[84:85], v[100:101] op_sel_hi:[1,0]
	v_max_f32_e32 v92, 0, v92
	v_max_f32_e32 v88, 0, v88
	v_max_f32_e32 v93, 0, v93
	v_max_f32_e32 v89, 0, v89
	v_max_f32_e32 v94, 0, v94
	v_max_f32_e32 v90, 0, v90
	v_max_f32_e32 v95, 0, v95
	v_max_f32_e32 v91, 0, v91
	v_max_f32_e32 v80, 0, v80
	v_max_f32_e32 v81, 0, v81
	v_max_f32_e32 v82, 0, v82
	v_max_f32_e32 v83, 0, v83
	v_max_f32_e32 v84, 0, v84
	v_max_f32_e32 v85, 0, v85
	v_max_f32_e32 v86, 0, v86
	v_max_f32_e32 v87, 0, v87
	v_mul_f32_e32 v92, v92, v92
	v_mul_f32_e32 v88, v88, v88
	v_mul_f32_e32 v93, v93, v93
	v_mul_f32_e32 v89, v89, v89
	v_mul_f32_e32 v94, v94, v94
	v_mul_f32_e32 v90, v90, v90
	v_mul_f32_e32 v95, v95, v95
	v_mul_f32_e32 v91, v91, v91
	v_mul_f32_e32 v100, v80, v80
	v_mul_f32_e32 v101, v81, v81
	v_mul_f32_e32 v102, v82, v82
	v_mul_f32_e32 v103, v83, v83
	v_cvt_pk_bf16_f32 v80, v92, v93
	v_cvt_pk_bf16_f32 v81, v94, v95
	v_cvt_pk_bf16_f32 v82, v88, v89
	v_cvt_pk_bf16_f32 v83, v90, v91
	v_mul_f32_e32 v84, v84, v84
	v_mul_f32_e32 v85, v85, v85
	v_mul_f32_e32 v86, v86, v86
	v_mul_f32_e32 v87, v87, v87
	global_store_dwordx4 v[98:99], v[80:83], off sc1
	s_nop 1
	v_cvt_pk_bf16_f32 v80, v84, v85
	v_cvt_pk_bf16_f32 v81, v86, v87
	v_cvt_pk_bf16_f32 v82, v100, v101
	v_cvt_pk_bf16_f32 v83, v102, v103
	global_store_dwordx4 v[98:99], v[80:83], off offset:256 sc1
	global_load_dwordx4 v[80:83], v[96:97], off
	s_nop 0
	global_load_dwordx4 v[84:87], v[96:97], off offset:16
	global_load_dwordx4 v[88:91], v[96:97], off offset:32
	global_load_dwordx4 v[92:95], v[96:97], off offset:48
	v_add_u32_e32 v96, 0x80, v146
	v_ashrrev_i32_e32 v97, 31, v96
	v_lshlrev_b64 v[98:99], 13, v[112:113]
	s_waitcnt vmcnt(2)
	v_pk_add_f32 v[82:83], v[82:83], v[86:87]
	v_pk_add_f32 v[80:81], v[80:81], v[84:85]
	s_waitcnt vmcnt(0)
	v_pk_add_f32 v[84:85], v[90:91], v[94:95]
	v_pk_add_f32 v[86:87], v[88:89], v[92:93]
	v_pk_add_f32 v[82:83], v[82:83], v[84:85]
	v_pk_add_f32 v[80:81], v[80:81], v[86:87]
	s_nop 0
	v_pk_mov_b32 v[84:85], v[80:81], v[82:83] op_sel:[1,0]
	v_mov_b32_e32 v81, v83
	v_pk_add_f32 v[80:81], v[84:85], v[80:81]
	v_lshl_add_u64 v[82:83], v[144:145], 0, v[98:99]
	v_add_f32_e32 v80, v80, v81
	v_fmamk_f32 v80, v80, 0x3a800000, v154
	v_mul_f32_e32 v81, 0x4b800000, v80
	v_cmp_gt_f32_e32 vcc, s48, v80
	s_nop 1
	v_cndmask_b32_e32 v80, v80, v81, vcc
	v_rsq_f32_e32 v84, v80
	v_lshlrev_b64 v[80:81], 6, v[96:97]
	v_lshl_add_u64 v[80:81], s[10:11], 0, v[80:81]
	v_mul_f32_e32 v85, 0x45800000, v84
	v_cndmask_b32_e32 v84, v84, v85, vcc
	v_pk_mul_f32 v[78:79], v[78:79], v[84:85] op_sel_hi:[1,0]
	v_pk_mul_f32 v[76:77], v[76:77], v[84:85] op_sel_hi:[1,0]
	v_pk_mul_f32 v[74:75], v[74:75], v[84:85] op_sel_hi:[1,0]
	v_pk_mul_f32 v[72:73], v[72:73], v[84:85] op_sel_hi:[1,0]
	v_pk_mul_f32 v[66:67], v[66:67], v[84:85] op_sel_hi:[1,0]
	v_pk_mul_f32 v[64:65], v[64:65], v[84:85] op_sel_hi:[1,0]
	v_pk_mul_f32 v[70:71], v[70:71], v[84:85] op_sel_hi:[1,0]
	v_pk_mul_f32 v[68:69], v[68:69], v[84:85] op_sel_hi:[1,0]
	v_max_f32_e32 v76, 0, v76
	v_max_f32_e32 v72, 0, v72
	v_max_f32_e32 v77, 0, v77
	v_max_f32_e32 v73, 0, v73
	v_max_f32_e32 v78, 0, v78
	v_max_f32_e32 v74, 0, v74
	v_max_f32_e32 v79, 0, v79
	v_max_f32_e32 v75, 0, v75
	v_max_f32_e32 v64, 0, v64
	v_max_f32_e32 v65, 0, v65
	v_max_f32_e32 v66, 0, v66
	v_max_f32_e32 v67, 0, v67
	v_max_f32_e32 v68, 0, v68
	v_max_f32_e32 v69, 0, v69
	v_max_f32_e32 v70, 0, v70
	v_max_f32_e32 v71, 0, v71
	v_mul_f32_e32 v76, v76, v76
	v_mul_f32_e32 v72, v72, v72
	v_mul_f32_e32 v77, v77, v77
	v_mul_f32_e32 v73, v73, v73
	v_mul_f32_e32 v78, v78, v78
	v_mul_f32_e32 v74, v74, v74
	v_mul_f32_e32 v79, v79, v79
	v_mul_f32_e32 v75, v75, v75
	v_mul_f32_e32 v84, v64, v64
	v_mul_f32_e32 v85, v65, v65
	v_mul_f32_e32 v86, v66, v66
	v_mul_f32_e32 v87, v67, v67
	v_cvt_pk_bf16_f32 v64, v76, v77
	v_cvt_pk_bf16_f32 v65, v78, v79
	v_cvt_pk_bf16_f32 v66, v72, v73
	v_cvt_pk_bf16_f32 v67, v74, v75
	v_mul_f32_e32 v68, v68, v68
	v_mul_f32_e32 v69, v69, v69
	v_mul_f32_e32 v70, v70, v70
	v_mul_f32_e32 v71, v71, v71
	global_store_dwordx4 v[82:83], v[64:67], off sc1
	s_nop 1
	v_cvt_pk_bf16_f32 v64, v68, v69
	v_cvt_pk_bf16_f32 v65, v70, v71
	v_cvt_pk_bf16_f32 v66, v84, v85
	v_cvt_pk_bf16_f32 v67, v86, v87
	global_store_dwordx4 v[82:83], v[64:67], off offset:256 sc1
	global_load_dwordx4 v[64:67], v[80:81], off
	s_nop 0
	global_load_dwordx4 v[68:71], v[80:81], off offset:16
	global_load_dwordx4 v[72:75], v[80:81], off offset:32
	global_load_dwordx4 v[76:79], v[80:81], off offset:48
	v_add_u32_e32 v80, 0x90, v146
	v_ashrrev_i32_e32 v81, 31, v80
	v_lshlrev_b64 v[82:83], 13, v[96:97]
	s_waitcnt vmcnt(2)
	v_pk_add_f32 v[66:67], v[66:67], v[70:71]
	v_pk_add_f32 v[64:65], v[64:65], v[68:69]
	s_waitcnt vmcnt(0)
	v_pk_add_f32 v[68:69], v[74:75], v[78:79]
	v_pk_add_f32 v[70:71], v[72:73], v[76:77]
	v_pk_add_f32 v[66:67], v[66:67], v[68:69]
	v_pk_add_f32 v[64:65], v[64:65], v[70:71]
	s_nop 0
	v_pk_mov_b32 v[68:69], v[64:65], v[66:67] op_sel:[1,0]
	v_mov_b32_e32 v65, v67
	v_pk_add_f32 v[64:65], v[68:69], v[64:65]
	v_lshl_add_u64 v[66:67], v[144:145], 0, v[82:83]
	v_add_f32_e32 v64, v64, v65
	v_fmamk_f32 v64, v64, 0x3a800000, v154
	v_mul_f32_e32 v65, 0x4b800000, v64
	v_cmp_gt_f32_e32 vcc, s48, v64
	s_nop 1
	v_cndmask_b32_e32 v64, v64, v65, vcc
	v_rsq_f32_e32 v68, v64
	v_lshlrev_b64 v[64:65], 6, v[80:81]
	v_lshl_add_u64 v[64:65], s[10:11], 0, v[64:65]
	v_mul_f32_e32 v69, 0x45800000, v68
	v_cndmask_b32_e32 v68, v68, v69, vcc
	v_pk_mul_f32 v[62:63], v[62:63], v[68:69] op_sel_hi:[1,0]
	v_pk_mul_f32 v[60:61], v[60:61], v[68:69] op_sel_hi:[1,0]
	v_pk_mul_f32 v[58:59], v[58:59], v[68:69] op_sel_hi:[1,0]
	v_pk_mul_f32 v[56:57], v[56:57], v[68:69] op_sel_hi:[1,0]
	v_pk_mul_f32 v[50:51], v[50:51], v[68:69] op_sel_hi:[1,0]
	v_pk_mul_f32 v[48:49], v[48:49], v[68:69] op_sel_hi:[1,0]
	v_pk_mul_f32 v[54:55], v[54:55], v[68:69] op_sel_hi:[1,0]
	v_pk_mul_f32 v[52:53], v[52:53], v[68:69] op_sel_hi:[1,0]
	v_max_f32_e32 v60, 0, v60
	v_max_f32_e32 v56, 0, v56
	v_max_f32_e32 v61, 0, v61
	v_max_f32_e32 v57, 0, v57
	v_max_f32_e32 v62, 0, v62
	v_max_f32_e32 v58, 0, v58
	v_max_f32_e32 v63, 0, v63
	v_max_f32_e32 v59, 0, v59
	v_max_f32_e32 v48, 0, v48
	v_max_f32_e32 v49, 0, v49
	v_max_f32_e32 v50, 0, v50
	v_max_f32_e32 v51, 0, v51
	v_max_f32_e32 v52, 0, v52
	v_max_f32_e32 v53, 0, v53
	v_max_f32_e32 v54, 0, v54
	v_max_f32_e32 v55, 0, v55
	v_mul_f32_e32 v60, v60, v60
	v_mul_f32_e32 v56, v56, v56
	v_mul_f32_e32 v61, v61, v61
	v_mul_f32_e32 v57, v57, v57
	v_mul_f32_e32 v62, v62, v62
	v_mul_f32_e32 v58, v58, v58
	v_mul_f32_e32 v63, v63, v63
	v_mul_f32_e32 v59, v59, v59
	v_mul_f32_e32 v68, v48, v48
	v_mul_f32_e32 v69, v49, v49
	v_mul_f32_e32 v70, v50, v50
	v_mul_f32_e32 v71, v51, v51
	v_cvt_pk_bf16_f32 v48, v60, v61
	v_cvt_pk_bf16_f32 v49, v62, v63
	v_cvt_pk_bf16_f32 v50, v56, v57
	v_cvt_pk_bf16_f32 v51, v58, v59
	v_mul_f32_e32 v52, v52, v52
	v_mul_f32_e32 v53, v53, v53
	v_mul_f32_e32 v54, v54, v54
	v_mul_f32_e32 v55, v55, v55
	global_store_dwordx4 v[66:67], v[48:51], off sc1
	s_nop 1
	v_cvt_pk_bf16_f32 v48, v52, v53
	v_cvt_pk_bf16_f32 v49, v54, v55
	v_cvt_pk_bf16_f32 v50, v68, v69
	v_cvt_pk_bf16_f32 v51, v70, v71
	global_store_dwordx4 v[66:67], v[48:51], off offset:256 sc1
	global_load_dwordx4 v[48:51], v[64:65], off
	s_nop 0
	global_load_dwordx4 v[52:55], v[64:65], off offset:16
	global_load_dwordx4 v[56:59], v[64:65], off offset:32
	global_load_dwordx4 v[60:63], v[64:65], off offset:48
	v_add_u32_e32 v64, 0xa0, v146
	v_ashrrev_i32_e32 v65, 31, v64
	v_lshlrev_b64 v[66:67], 13, v[80:81]
	s_waitcnt vmcnt(2)
	v_pk_add_f32 v[50:51], v[50:51], v[54:55]
	v_pk_add_f32 v[48:49], v[48:49], v[52:53]
	s_waitcnt vmcnt(0)
	v_pk_add_f32 v[52:53], v[58:59], v[62:63]
	v_pk_add_f32 v[54:55], v[56:57], v[60:61]
	v_pk_add_f32 v[50:51], v[50:51], v[52:53]
	v_pk_add_f32 v[48:49], v[48:49], v[54:55]
	s_nop 0
	v_pk_mov_b32 v[52:53], v[48:49], v[50:51] op_sel:[1,0]
	v_mov_b32_e32 v49, v51
	v_pk_add_f32 v[48:49], v[52:53], v[48:49]
	v_lshl_add_u64 v[50:51], v[144:145], 0, v[66:67]
	v_add_f32_e32 v48, v48, v49
	v_fmamk_f32 v48, v48, 0x3a800000, v154
	v_mul_f32_e32 v49, 0x4b800000, v48
	v_cmp_gt_f32_e32 vcc, s48, v48
	s_nop 1
	v_cndmask_b32_e32 v48, v48, v49, vcc
	v_rsq_f32_e32 v52, v48
	v_lshlrev_b64 v[48:49], 6, v[64:65]
	v_lshl_add_u64 v[48:49], s[10:11], 0, v[48:49]
	v_mul_f32_e32 v53, 0x45800000, v52
	v_cndmask_b32_e32 v52, v52, v53, vcc
	v_pk_mul_f32 v[46:47], v[46:47], v[52:53] op_sel_hi:[1,0]
	v_pk_mul_f32 v[44:45], v[44:45], v[52:53] op_sel_hi:[1,0]
	v_pk_mul_f32 v[42:43], v[42:43], v[52:53] op_sel_hi:[1,0]
	v_pk_mul_f32 v[40:41], v[40:41], v[52:53] op_sel_hi:[1,0]
	v_pk_mul_f32 v[34:35], v[34:35], v[52:53] op_sel_hi:[1,0]
	v_pk_mul_f32 v[32:33], v[32:33], v[52:53] op_sel_hi:[1,0]
	v_pk_mul_f32 v[38:39], v[38:39], v[52:53] op_sel_hi:[1,0]
	v_pk_mul_f32 v[36:37], v[36:37], v[52:53] op_sel_hi:[1,0]
	v_max_f32_e32 v44, 0, v44
	v_max_f32_e32 v40, 0, v40
	v_max_f32_e32 v45, 0, v45
	v_max_f32_e32 v41, 0, v41
	v_max_f32_e32 v46, 0, v46
	v_max_f32_e32 v42, 0, v42
	v_max_f32_e32 v47, 0, v47
	v_max_f32_e32 v43, 0, v43
	v_max_f32_e32 v32, 0, v32
	v_max_f32_e32 v33, 0, v33
	v_max_f32_e32 v34, 0, v34
	v_max_f32_e32 v35, 0, v35
	v_max_f32_e32 v36, 0, v36
	v_max_f32_e32 v37, 0, v37
	v_max_f32_e32 v38, 0, v38
	v_max_f32_e32 v39, 0, v39
	v_mul_f32_e32 v44, v44, v44
	v_mul_f32_e32 v40, v40, v40
	v_mul_f32_e32 v45, v45, v45
	v_mul_f32_e32 v41, v41, v41
	v_mul_f32_e32 v46, v46, v46
	v_mul_f32_e32 v42, v42, v42
	v_mul_f32_e32 v47, v47, v47
	v_mul_f32_e32 v43, v43, v43
	v_mul_f32_e32 v52, v32, v32
	v_mul_f32_e32 v53, v33, v33
	v_mul_f32_e32 v54, v34, v34
	v_mul_f32_e32 v55, v35, v35
	v_cvt_pk_bf16_f32 v32, v44, v45
	v_cvt_pk_bf16_f32 v33, v46, v47
	v_cvt_pk_bf16_f32 v34, v40, v41
	v_cvt_pk_bf16_f32 v35, v42, v43
	v_mul_f32_e32 v36, v36, v36
	v_mul_f32_e32 v37, v37, v37
	v_mul_f32_e32 v38, v38, v38
	v_mul_f32_e32 v39, v39, v39
	global_store_dwordx4 v[50:51], v[32:35], off sc1
	s_nop 1
	v_cvt_pk_bf16_f32 v32, v36, v37
	v_cvt_pk_bf16_f32 v33, v38, v39
	v_cvt_pk_bf16_f32 v34, v52, v53
	v_cvt_pk_bf16_f32 v35, v54, v55
	global_store_dwordx4 v[50:51], v[32:35], off offset:256 sc1
	global_load_dwordx4 v[32:35], v[48:49], off
	s_nop 0
	global_load_dwordx4 v[36:39], v[48:49], off offset:16
	global_load_dwordx4 v[40:43], v[48:49], off offset:32
	global_load_dwordx4 v[44:47], v[48:49], off offset:48
	v_add_u32_e32 v48, 0xb0, v146
	v_ashrrev_i32_e32 v49, 31, v48
	v_lshlrev_b64 v[50:51], 13, v[64:65]
	s_waitcnt vmcnt(2)
	v_pk_add_f32 v[34:35], v[34:35], v[38:39]
	v_pk_add_f32 v[32:33], v[32:33], v[36:37]
	s_waitcnt vmcnt(0)
	v_pk_add_f32 v[36:37], v[42:43], v[46:47]
	v_pk_add_f32 v[38:39], v[40:41], v[44:45]
	v_pk_add_f32 v[34:35], v[34:35], v[36:37]
	v_pk_add_f32 v[32:33], v[32:33], v[38:39]
	s_nop 0
	v_pk_mov_b32 v[36:37], v[32:33], v[34:35] op_sel:[1,0]
	v_mov_b32_e32 v33, v35
	v_pk_add_f32 v[32:33], v[36:37], v[32:33]
	v_lshl_add_u64 v[34:35], v[144:145], 0, v[50:51]
	v_add_f32_e32 v32, v32, v33
	v_fmamk_f32 v32, v32, 0x3a800000, v154
	v_mul_f32_e32 v33, 0x4b800000, v32
	v_cmp_gt_f32_e32 vcc, s48, v32
	s_nop 1
	v_cndmask_b32_e32 v32, v32, v33, vcc
	v_rsq_f32_e32 v36, v32
	v_lshlrev_b64 v[32:33], 6, v[48:49]
	v_lshl_add_u64 v[32:33], s[10:11], 0, v[32:33]
	v_mul_f32_e32 v37, 0x45800000, v36
	v_cndmask_b32_e32 v36, v36, v37, vcc
	v_pk_mul_f32 v[30:31], v[30:31], v[36:37] op_sel_hi:[1,0]
	v_pk_mul_f32 v[28:29], v[28:29], v[36:37] op_sel_hi:[1,0]
	v_pk_mul_f32 v[26:27], v[26:27], v[36:37] op_sel_hi:[1,0]
	v_pk_mul_f32 v[24:25], v[24:25], v[36:37] op_sel_hi:[1,0]
	v_pk_mul_f32 v[18:19], v[18:19], v[36:37] op_sel_hi:[1,0]
	v_pk_mul_f32 v[16:17], v[16:17], v[36:37] op_sel_hi:[1,0]
	v_pk_mul_f32 v[22:23], v[22:23], v[36:37] op_sel_hi:[1,0]
	v_pk_mul_f32 v[20:21], v[20:21], v[36:37] op_sel_hi:[1,0]
	v_max_f32_e32 v28, 0, v28
	v_max_f32_e32 v24, 0, v24
	v_max_f32_e32 v29, 0, v29
	v_max_f32_e32 v25, 0, v25
	v_max_f32_e32 v30, 0, v30
	v_max_f32_e32 v26, 0, v26
	v_max_f32_e32 v31, 0, v31
	v_max_f32_e32 v27, 0, v27
	v_max_f32_e32 v16, 0, v16
	v_max_f32_e32 v17, 0, v17
	v_max_f32_e32 v18, 0, v18
	v_max_f32_e32 v19, 0, v19
	v_max_f32_e32 v20, 0, v20
	v_max_f32_e32 v21, 0, v21
	v_max_f32_e32 v22, 0, v22
	v_max_f32_e32 v23, 0, v23
	v_mul_f32_e32 v28, v28, v28
	v_mul_f32_e32 v24, v24, v24
	v_mul_f32_e32 v29, v29, v29
	v_mul_f32_e32 v25, v25, v25
	v_mul_f32_e32 v30, v30, v30
	v_mul_f32_e32 v26, v26, v26
	v_mul_f32_e32 v31, v31, v31
	v_mul_f32_e32 v27, v27, v27
	v_mul_f32_e32 v36, v16, v16
	v_mul_f32_e32 v37, v17, v17
	v_mul_f32_e32 v38, v18, v18
	v_mul_f32_e32 v39, v19, v19
	v_cvt_pk_bf16_f32 v16, v28, v29
	v_cvt_pk_bf16_f32 v17, v30, v31
	v_cvt_pk_bf16_f32 v18, v24, v25
	v_cvt_pk_bf16_f32 v19, v26, v27
	v_mul_f32_e32 v20, v20, v20
	v_mul_f32_e32 v21, v21, v21
	v_mul_f32_e32 v22, v22, v22
	v_mul_f32_e32 v23, v23, v23
	global_store_dwordx4 v[34:35], v[16:19], off sc1
	s_andn2_b64 vcc, exec, s[4:5]
	s_mov_b64 s[4:5], -1
	v_cvt_pk_bf16_f32 v16, v20, v21
	v_cvt_pk_bf16_f32 v17, v22, v23
	v_cvt_pk_bf16_f32 v18, v36, v37
	v_cvt_pk_bf16_f32 v19, v38, v39
	global_store_dwordx4 v[34:35], v[16:19], off offset:256 sc1
	global_load_dwordx4 v[16:19], v[32:33], off
	s_nop 0
	global_load_dwordx4 v[20:23], v[32:33], off offset:16
	global_load_dwordx4 v[24:27], v[32:33], off offset:32
	global_load_dwordx4 v[28:31], v[32:33], off offset:48
	s_waitcnt vmcnt(2)
	v_pk_add_f32 v[18:19], v[18:19], v[22:23]
	v_pk_add_f32 v[16:17], v[16:17], v[20:21]
	s_waitcnt vmcnt(0)
	v_pk_add_f32 v[20:21], v[26:27], v[30:31]
	v_pk_add_f32 v[22:23], v[24:25], v[28:29]
	v_pk_add_f32 v[18:19], v[18:19], v[20:21]
	v_pk_add_f32 v[16:17], v[16:17], v[22:23]
	s_nop 0
	v_pk_mov_b32 v[20:21], v[16:17], v[18:19] op_sel:[1,0]
	v_mov_b32_e32 v17, v19
	v_pk_add_f32 v[16:17], v[20:21], v[16:17]
	s_nop 0
	v_add_f32_e32 v16, v16, v17
	v_fmamk_f32 v16, v16, 0x3a800000, v154
	v_mul_f32_e32 v17, 0x4b800000, v16
	v_cmp_gt_f32_e64 s[6:7], s48, v16
	s_nop 1
	v_cndmask_b32_e64 v16, v16, v17, s[6:7]
	v_rsq_f32_e32 v18, v16
	v_lshlrev_b64 v[16:17], 13, v[48:49]
	v_lshl_add_u64 v[16:17], v[144:145], 0, v[16:17]
	v_mul_f32_e32 v19, 0x45800000, v18
	v_cndmask_b32_e64 v18, v18, v19, s[6:7]
	v_pk_mul_f32 v[14:15], v[14:15], v[18:19] op_sel_hi:[1,0]
	v_pk_mul_f32 v[12:13], v[12:13], v[18:19] op_sel_hi:[1,0]
	v_pk_mul_f32 v[10:11], v[10:11], v[18:19] op_sel_hi:[1,0]
	v_pk_mul_f32 v[8:9], v[8:9], v[18:19] op_sel_hi:[1,0]
	v_pk_mul_f32 v[2:3], v[2:3], v[18:19] op_sel_hi:[1,0]
	v_pk_mul_f32 v[0:1], v[0:1], v[18:19] op_sel_hi:[1,0]
	v_pk_mul_f32 v[6:7], v[6:7], v[18:19] op_sel_hi:[1,0]
	v_pk_mul_f32 v[4:5], v[4:5], v[18:19] op_sel_hi:[1,0]
	v_max_f32_e32 v12, 0, v12
	v_max_f32_e32 v8, 0, v8
	v_max_f32_e32 v13, 0, v13
	v_max_f32_e32 v9, 0, v9
	v_max_f32_e32 v14, 0, v14
	v_max_f32_e32 v10, 0, v10
	v_max_f32_e32 v15, 0, v15
	v_max_f32_e32 v11, 0, v11
	v_max_f32_e32 v0, 0, v0
	v_max_f32_e32 v1, 0, v1
	v_max_f32_e32 v2, 0, v2
	v_max_f32_e32 v3, 0, v3
	v_max_f32_e32 v4, 0, v4
	v_max_f32_e32 v5, 0, v5
	v_max_f32_e32 v6, 0, v6
	v_max_f32_e32 v7, 0, v7
	v_mul_f32_e32 v12, v12, v12
	v_mul_f32_e32 v8, v8, v8
	v_mul_f32_e32 v13, v13, v13
	v_mul_f32_e32 v9, v9, v9
	v_mul_f32_e32 v14, v14, v14
	v_mul_f32_e32 v10, v10, v10
	v_mul_f32_e32 v15, v15, v15
	v_mul_f32_e32 v11, v11, v11
	v_mul_f32_e32 v18, v0, v0
	v_mul_f32_e32 v19, v1, v1
	v_mul_f32_e32 v20, v2, v2
	v_mul_f32_e32 v21, v3, v3
	v_cvt_pk_bf16_f32 v0, v12, v13
	v_cvt_pk_bf16_f32 v1, v14, v15
	v_cvt_pk_bf16_f32 v2, v8, v9
	v_cvt_pk_bf16_f32 v3, v10, v11
	v_mul_f32_e32 v4, v4, v4
	v_mul_f32_e32 v5, v5, v5
	v_mul_f32_e32 v6, v6, v6
	v_mul_f32_e32 v7, v7, v7
	global_store_dwordx4 v[16:17], v[0:3], off sc1
	s_nop 1
	v_cvt_pk_bf16_f32 v0, v4, v5
	v_cvt_pk_bf16_f32 v1, v6, v7
	v_cvt_pk_bf16_f32 v2, v18, v19
	v_cvt_pk_bf16_f32 v3, v20, v21
	global_store_dwordx4 v[16:17], v[0:3], off offset:256 sc1
	s_cbranch_vccnz .LBB0_691
	s_andn2_b64 vcc, exec, s[2:3]
	s_cbranch_vccnz .LBB0_690
	s_barrier
	s_branch .LBB0_690

.LBB0_1368:
	v_lshl_add_u32 v146, s6, 8, v148
	v_ashrrev_i32_e32 v147, 31, v146
	v_lshlrev_b64 v[144:145], 6, v[146:147]
	v_lshl_add_u64 v[144:145], s[10:11], 0, v[144:145]
	global_load_dwordx4 v[156:159], v[144:145], off
	global_load_dwordx4 v[160:163], v[144:145], off offset:16
	global_load_dwordx4 v[164:167], v[144:145], off offset:32
	global_load_dwordx4 v[168:171], v[144:145], off offset:48
	v_lshlrev_b64 v[174:175], 13, v[146:147]
	v_lshl_or_b32 v144, s7, 8, v150
	v_ashrrev_i32_e32 v145, 31, v144
	v_or_b32_e32 v172, 16, v146
	v_lshl_add_u64 v[144:145], v[144:145], 1, s[8:9]
	v_ashrrev_i32_e32 v173, 31, v172
	s_waitcnt vmcnt(0)
	v_pk_add_f32 v[158:159], v[158:159], v[162:163]
	v_pk_add_f32 v[156:157], v[156:157], v[160:161]
	v_pk_add_f32 v[160:161], v[166:167], v[170:171]
	v_pk_add_f32 v[162:163], v[164:165], v[168:169]
	v_pk_add_f32 v[158:159], v[158:159], v[160:161]
	v_pk_add_f32 v[156:157], v[156:157], v[162:163]
	s_nop 0
	v_pk_mov_b32 v[160:161], v[156:157], v[158:159] op_sel:[1,0]
	v_mov_b32_e32 v157, v159
	v_pk_add_f32 v[156:157], v[160:161], v[156:157]
	v_lshlrev_b64 v[158:159], 6, v[172:173]
	v_add_f32_e32 v147, v156, v157
	v_fmamk_f32 v147, v147, 0x3a800000, v154
	v_mul_f32_e32 v155, 0x4b800000, v147
	v_cmp_gt_f32_e32 vcc, s48, v147
	v_lshl_add_u64 v[156:157], v[144:145], 0, v[174:175]
	v_lshl_add_u64 v[158:159], s[10:11], 0, v[158:159]
	v_cndmask_b32_e32 v147, v147, v155, vcc
	v_rsq_f32_e32 v147, v147
	s_nop 0
	v_mul_f32_e32 v155, 0x45800000, v147
	v_cndmask_b32_e32 v160, v147, v155, vcc
	v_pk_mul_f32 v[126:127], v[126:127], v[160:161] op_sel_hi:[1,0]
	v_pk_mul_f32 v[124:125], v[124:125], v[160:161] op_sel_hi:[1,0]
	v_pk_mul_f32 v[122:123], v[122:123], v[160:161] op_sel_hi:[1,0]
	v_pk_mul_f32 v[120:121], v[120:121], v[160:161] op_sel_hi:[1,0]
	v_pk_mul_f32 v[114:115], v[114:115], v[160:161] op_sel_hi:[1,0]
	v_pk_mul_f32 v[112:113], v[112:113], v[160:161] op_sel_hi:[1,0]
	v_pk_mul_f32 v[118:119], v[118:119], v[160:161] op_sel_hi:[1,0]
	v_pk_mul_f32 v[116:117], v[116:117], v[160:161] op_sel_hi:[1,0]
	v_max_f32_e32 v124, 0, v124
	v_max_f32_e32 v120, 0, v120
	v_max_f32_e32 v125, 0, v125
	v_max_f32_e32 v121, 0, v121
	v_max_f32_e32 v126, 0, v126
	v_max_f32_e32 v122, 0, v122
	v_max_f32_e32 v127, 0, v127
	v_max_f32_e32 v123, 0, v123
	v_max_f32_e32 v112, 0, v112
	v_max_f32_e32 v113, 0, v113
	v_max_f32_e32 v114, 0, v114
	v_max_f32_e32 v115, 0, v115
	v_max_f32_e32 v116, 0, v116
	v_max_f32_e32 v117, 0, v117
	v_max_f32_e32 v118, 0, v118
	v_max_f32_e32 v119, 0, v119
	v_mul_f32_e32 v124, v124, v124
	v_mul_f32_e32 v120, v120, v120
	v_mul_f32_e32 v125, v125, v125
	v_mul_f32_e32 v121, v121, v121
	v_mul_f32_e32 v126, v126, v126
	v_mul_f32_e32 v122, v122, v122
	v_mul_f32_e32 v127, v127, v127
	v_mul_f32_e32 v123, v123, v123
	v_mul_f32_e32 v147, v112, v112
	v_mul_f32_e32 v155, v113, v113
	v_mul_f32_e32 v160, v114, v114
	v_mul_f32_e32 v161, v115, v115
	v_cvt_pk_bf16_f32 v112, v124, v125
	v_cvt_pk_bf16_f32 v113, v126, v127
	v_cvt_pk_bf16_f32 v114, v120, v121
	v_cvt_pk_bf16_f32 v115, v122, v123
	v_mul_f32_e32 v116, v116, v116
	v_mul_f32_e32 v117, v117, v117
	v_mul_f32_e32 v118, v118, v118
	v_mul_f32_e32 v119, v119, v119
	global_store_dwordx4 v[156:157], v[112:115], off sc1
	s_nop 1
	v_cvt_pk_bf16_f32 v112, v116, v117
	v_cvt_pk_bf16_f32 v113, v118, v119
	v_cvt_pk_bf16_f32 v114, v147, v155
	v_cvt_pk_bf16_f32 v115, v160, v161
	global_store_dwordx4 v[156:157], v[112:115], off offset:256 sc1
	global_load_dwordx4 v[112:115], v[158:159], off
	s_nop 0
	global_load_dwordx4 v[116:119], v[158:159], off offset:16
	global_load_dwordx4 v[120:123], v[158:159], off offset:32
	global_load_dwordx4 v[124:127], v[158:159], off offset:48
	v_or_b32_e32 v156, 32, v146
	v_ashrrev_i32_e32 v157, 31, v156
	v_lshlrev_b64 v[158:159], 13, v[172:173]
	s_waitcnt vmcnt(2)
	v_pk_add_f32 v[114:115], v[114:115], v[118:119]
	v_pk_add_f32 v[112:113], v[112:113], v[116:117]
	s_waitcnt vmcnt(0)
	v_pk_add_f32 v[116:117], v[122:123], v[126:127]
	v_pk_add_f32 v[118:119], v[120:121], v[124:125]
	v_pk_add_f32 v[114:115], v[114:115], v[116:117]
	v_pk_add_f32 v[112:113], v[112:113], v[118:119]
	s_nop 0
	v_pk_mov_b32 v[116:117], v[112:113], v[114:115] op_sel:[1,0]
	v_mov_b32_e32 v113, v115
	v_pk_add_f32 v[112:113], v[116:117], v[112:113]
	v_lshl_add_u64 v[114:115], v[144:145], 0, v[158:159]
	v_add_f32_e32 v112, v112, v113
	v_fmamk_f32 v112, v112, 0x3a800000, v154
	v_mul_f32_e32 v113, 0x4b800000, v112
	v_cmp_gt_f32_e32 vcc, s48, v112
	s_nop 1
	v_cndmask_b32_e32 v112, v112, v113, vcc
	v_rsq_f32_e32 v116, v112
	v_lshlrev_b64 v[112:113], 6, v[156:157]
	v_lshl_add_u64 v[112:113], s[10:11], 0, v[112:113]
	v_mul_f32_e32 v117, 0x45800000, v116
	v_cndmask_b32_e32 v116, v116, v117, vcc
	v_pk_mul_f32 v[110:111], v[110:111], v[116:117] op_sel_hi:[1,0]
	v_pk_mul_f32 v[108:109], v[108:109], v[116:117] op_sel_hi:[1,0]
	v_pk_mul_f32 v[106:107], v[106:107], v[116:117] op_sel_hi:[1,0]
	v_pk_mul_f32 v[104:105], v[104:105], v[116:117] op_sel_hi:[1,0]
	v_pk_mul_f32 v[98:99], v[98:99], v[116:117] op_sel_hi:[1,0]
	v_pk_mul_f32 v[96:97], v[96:97], v[116:117] op_sel_hi:[1,0]
	v_pk_mul_f32 v[102:103], v[102:103], v[116:117] op_sel_hi:[1,0]
	v_pk_mul_f32 v[100:101], v[100:101], v[116:117] op_sel_hi:[1,0]
	v_max_f32_e32 v108, 0, v108
	v_max_f32_e32 v104, 0, v104
	v_max_f32_e32 v109, 0, v109
	v_max_f32_e32 v105, 0, v105
	v_max_f32_e32 v110, 0, v110
	v_max_f32_e32 v106, 0, v106
	v_max_f32_e32 v111, 0, v111
	v_max_f32_e32 v107, 0, v107
	v_max_f32_e32 v96, 0, v96
	v_max_f32_e32 v97, 0, v97
	v_max_f32_e32 v98, 0, v98
	v_max_f32_e32 v99, 0, v99
	v_max_f32_e32 v100, 0, v100
	v_max_f32_e32 v101, 0, v101
	v_max_f32_e32 v102, 0, v102
	v_max_f32_e32 v103, 0, v103
	v_mul_f32_e32 v108, v108, v108
	v_mul_f32_e32 v104, v104, v104
	v_mul_f32_e32 v109, v109, v109
	v_mul_f32_e32 v105, v105, v105
	v_mul_f32_e32 v110, v110, v110
	v_mul_f32_e32 v106, v106, v106
	v_mul_f32_e32 v111, v111, v111
	v_mul_f32_e32 v107, v107, v107
	v_mul_f32_e32 v116, v96, v96
	v_mul_f32_e32 v117, v97, v97
	v_mul_f32_e32 v118, v98, v98
	v_mul_f32_e32 v119, v99, v99
	v_cvt_pk_bf16_f32 v96, v108, v109
	v_cvt_pk_bf16_f32 v97, v110, v111
	v_cvt_pk_bf16_f32 v98, v104, v105
	v_cvt_pk_bf16_f32 v99, v106, v107
	v_mul_f32_e32 v100, v100, v100
	v_mul_f32_e32 v101, v101, v101
	v_mul_f32_e32 v102, v102, v102
	v_mul_f32_e32 v103, v103, v103
	global_store_dwordx4 v[114:115], v[96:99], off sc1
	s_nop 1
	v_cvt_pk_bf16_f32 v96, v100, v101
	v_cvt_pk_bf16_f32 v97, v102, v103
	v_cvt_pk_bf16_f32 v98, v116, v117
	v_cvt_pk_bf16_f32 v99, v118, v119
	global_store_dwordx4 v[114:115], v[96:99], off offset:256 sc1
	global_load_dwordx4 v[96:99], v[112:113], off
	s_nop 0
	global_load_dwordx4 v[100:103], v[112:113], off offset:16
	global_load_dwordx4 v[104:107], v[112:113], off offset:32
	global_load_dwordx4 v[108:111], v[112:113], off offset:48
	v_or_b32_e32 v112, 48, v146
	v_ashrrev_i32_e32 v113, 31, v112
	v_lshlrev_b64 v[114:115], 13, v[156:157]
	s_waitcnt vmcnt(2)
	v_pk_add_f32 v[98:99], v[98:99], v[102:103]
	v_pk_add_f32 v[96:97], v[96:97], v[100:101]
	s_waitcnt vmcnt(0)
	v_pk_add_f32 v[100:101], v[106:107], v[110:111]
	v_pk_add_f32 v[102:103], v[104:105], v[108:109]
	v_pk_add_f32 v[98:99], v[98:99], v[100:101]
	v_pk_add_f32 v[96:97], v[96:97], v[102:103]
	s_nop 0
	v_pk_mov_b32 v[100:101], v[96:97], v[98:99] op_sel:[1,0]
	v_mov_b32_e32 v97, v99
	v_pk_add_f32 v[96:97], v[100:101], v[96:97]
	v_lshl_add_u64 v[98:99], v[144:145], 0, v[114:115]
	v_add_f32_e32 v96, v96, v97
	v_fmamk_f32 v96, v96, 0x3a800000, v154
	v_mul_f32_e32 v97, 0x4b800000, v96
	v_cmp_gt_f32_e32 vcc, s48, v96
	s_nop 1
	v_cndmask_b32_e32 v96, v96, v97, vcc
	v_rsq_f32_e32 v100, v96
	v_lshlrev_b64 v[96:97], 6, v[112:113]
	v_lshl_add_u64 v[96:97], s[10:11], 0, v[96:97]
	v_mul_f32_e32 v101, 0x45800000, v100
	v_cndmask_b32_e32 v100, v100, v101, vcc
	v_pk_mul_f32 v[94:95], v[94:95], v[100:101] op_sel_hi:[1,0]
	v_pk_mul_f32 v[92:93], v[92:93], v[100:101] op_sel_hi:[1,0]
	v_pk_mul_f32 v[90:91], v[90:91], v[100:101] op_sel_hi:[1,0]
	v_pk_mul_f32 v[88:89], v[88:89], v[100:101] op_sel_hi:[1,0]
	v_pk_mul_f32 v[82:83], v[82:83], v[100:101] op_sel_hi:[1,0]
	v_pk_mul_f32 v[80:81], v[80:81], v[100:101] op_sel_hi:[1,0]
	v_pk_mul_f32 v[86:87], v[86:87], v[100:101] op_sel_hi:[1,0]
	v_pk_mul_f32 v[84:85], v[84:85], v[100:101] op_sel_hi:[1,0]
	v_max_f32_e32 v92, 0, v92
	v_max_f32_e32 v88, 0, v88
	v_max_f32_e32 v93, 0, v93
	v_max_f32_e32 v89, 0, v89
	v_max_f32_e32 v94, 0, v94
	v_max_f32_e32 v90, 0, v90
	v_max_f32_e32 v95, 0, v95
	v_max_f32_e32 v91, 0, v91
	v_max_f32_e32 v80, 0, v80
	v_max_f32_e32 v81, 0, v81
	v_max_f32_e32 v82, 0, v82
	v_max_f32_e32 v83, 0, v83
	v_max_f32_e32 v84, 0, v84
	v_max_f32_e32 v85, 0, v85
	v_max_f32_e32 v86, 0, v86
	v_max_f32_e32 v87, 0, v87
	v_mul_f32_e32 v92, v92, v92
	v_mul_f32_e32 v88, v88, v88
	v_mul_f32_e32 v93, v93, v93
	v_mul_f32_e32 v89, v89, v89
	v_mul_f32_e32 v94, v94, v94
	v_mul_f32_e32 v90, v90, v90
	v_mul_f32_e32 v95, v95, v95
	v_mul_f32_e32 v91, v91, v91
	v_mul_f32_e32 v100, v80, v80
	v_mul_f32_e32 v101, v81, v81
	v_mul_f32_e32 v102, v82, v82
	v_mul_f32_e32 v103, v83, v83
	v_cvt_pk_bf16_f32 v80, v92, v93
	v_cvt_pk_bf16_f32 v81, v94, v95
	v_cvt_pk_bf16_f32 v82, v88, v89
	v_cvt_pk_bf16_f32 v83, v90, v91
	v_mul_f32_e32 v84, v84, v84
	v_mul_f32_e32 v85, v85, v85
	v_mul_f32_e32 v86, v86, v86
	v_mul_f32_e32 v87, v87, v87
	global_store_dwordx4 v[98:99], v[80:83], off sc1
	s_nop 1
	v_cvt_pk_bf16_f32 v80, v84, v85
	v_cvt_pk_bf16_f32 v81, v86, v87
	v_cvt_pk_bf16_f32 v82, v100, v101
	v_cvt_pk_bf16_f32 v83, v102, v103
	global_store_dwordx4 v[98:99], v[80:83], off offset:256 sc1
	global_load_dwordx4 v[80:83], v[96:97], off
	s_nop 0
	global_load_dwordx4 v[84:87], v[96:97], off offset:16
	global_load_dwordx4 v[88:91], v[96:97], off offset:32
	global_load_dwordx4 v[92:95], v[96:97], off offset:48
	v_add_u32_e32 v96, 0x80, v146
	v_ashrrev_i32_e32 v97, 31, v96
	v_lshlrev_b64 v[98:99], 13, v[112:113]
	s_waitcnt vmcnt(2)
	v_pk_add_f32 v[82:83], v[82:83], v[86:87]
	v_pk_add_f32 v[80:81], v[80:81], v[84:85]
	s_waitcnt vmcnt(0)
	v_pk_add_f32 v[84:85], v[90:91], v[94:95]
	v_pk_add_f32 v[86:87], v[88:89], v[92:93]
	v_pk_add_f32 v[82:83], v[82:83], v[84:85]
	v_pk_add_f32 v[80:81], v[80:81], v[86:87]
	s_nop 0
	v_pk_mov_b32 v[84:85], v[80:81], v[82:83] op_sel:[1,0]
	v_mov_b32_e32 v81, v83
	v_pk_add_f32 v[80:81], v[84:85], v[80:81]
	v_lshl_add_u64 v[82:83], v[144:145], 0, v[98:99]
	v_add_f32_e32 v80, v80, v81
	v_fmamk_f32 v80, v80, 0x3a800000, v154
	v_mul_f32_e32 v81, 0x4b800000, v80
	v_cmp_gt_f32_e32 vcc, s48, v80
	s_nop 1
	v_cndmask_b32_e32 v80, v80, v81, vcc
	v_rsq_f32_e32 v84, v80
	v_lshlrev_b64 v[80:81], 6, v[96:97]
	v_lshl_add_u64 v[80:81], s[10:11], 0, v[80:81]
	v_mul_f32_e32 v85, 0x45800000, v84
	v_cndmask_b32_e32 v84, v84, v85, vcc
	v_pk_mul_f32 v[78:79], v[78:79], v[84:85] op_sel_hi:[1,0]
	v_pk_mul_f32 v[76:77], v[76:77], v[84:85] op_sel_hi:[1,0]
	v_pk_mul_f32 v[74:75], v[74:75], v[84:85] op_sel_hi:[1,0]
	v_pk_mul_f32 v[72:73], v[72:73], v[84:85] op_sel_hi:[1,0]
	v_pk_mul_f32 v[66:67], v[66:67], v[84:85] op_sel_hi:[1,0]
	v_pk_mul_f32 v[64:65], v[64:65], v[84:85] op_sel_hi:[1,0]
	v_pk_mul_f32 v[70:71], v[70:71], v[84:85] op_sel_hi:[1,0]
	v_pk_mul_f32 v[68:69], v[68:69], v[84:85] op_sel_hi:[1,0]
	v_max_f32_e32 v76, 0, v76
	v_max_f32_e32 v72, 0, v72
	v_max_f32_e32 v77, 0, v77
	v_max_f32_e32 v73, 0, v73
	v_max_f32_e32 v78, 0, v78
	v_max_f32_e32 v74, 0, v74
	v_max_f32_e32 v79, 0, v79
	v_max_f32_e32 v75, 0, v75
	v_max_f32_e32 v64, 0, v64
	v_max_f32_e32 v65, 0, v65
	v_max_f32_e32 v66, 0, v66
	v_max_f32_e32 v67, 0, v67
	v_max_f32_e32 v68, 0, v68
	v_max_f32_e32 v69, 0, v69
	v_max_f32_e32 v70, 0, v70
	v_max_f32_e32 v71, 0, v71
	v_mul_f32_e32 v76, v76, v76
	v_mul_f32_e32 v72, v72, v72
	v_mul_f32_e32 v77, v77, v77
	v_mul_f32_e32 v73, v73, v73
	v_mul_f32_e32 v78, v78, v78
	v_mul_f32_e32 v74, v74, v74
	v_mul_f32_e32 v79, v79, v79
	v_mul_f32_e32 v75, v75, v75
	v_mul_f32_e32 v84, v64, v64
	v_mul_f32_e32 v85, v65, v65
	v_mul_f32_e32 v86, v66, v66
	v_mul_f32_e32 v87, v67, v67
	v_cvt_pk_bf16_f32 v64, v76, v77
	v_cvt_pk_bf16_f32 v65, v78, v79
	v_cvt_pk_bf16_f32 v66, v72, v73
	v_cvt_pk_bf16_f32 v67, v74, v75
	v_mul_f32_e32 v68, v68, v68
	v_mul_f32_e32 v69, v69, v69
	v_mul_f32_e32 v70, v70, v70
	v_mul_f32_e32 v71, v71, v71
	global_store_dwordx4 v[82:83], v[64:67], off sc1
	s_nop 1
	v_cvt_pk_bf16_f32 v64, v68, v69
	v_cvt_pk_bf16_f32 v65, v70, v71
	v_cvt_pk_bf16_f32 v66, v84, v85
	v_cvt_pk_bf16_f32 v67, v86, v87
	global_store_dwordx4 v[82:83], v[64:67], off offset:256 sc1
	global_load_dwordx4 v[64:67], v[80:81], off
	s_nop 0
	global_load_dwordx4 v[68:71], v[80:81], off offset:16
	global_load_dwordx4 v[72:75], v[80:81], off offset:32
	global_load_dwordx4 v[76:79], v[80:81], off offset:48
	v_add_u32_e32 v80, 0x90, v146
	v_ashrrev_i32_e32 v81, 31, v80
	v_lshlrev_b64 v[82:83], 13, v[96:97]
	s_waitcnt vmcnt(2)
	v_pk_add_f32 v[66:67], v[66:67], v[70:71]
	v_pk_add_f32 v[64:65], v[64:65], v[68:69]
	s_waitcnt vmcnt(0)
	v_pk_add_f32 v[68:69], v[74:75], v[78:79]
	v_pk_add_f32 v[70:71], v[72:73], v[76:77]
	v_pk_add_f32 v[66:67], v[66:67], v[68:69]
	v_pk_add_f32 v[64:65], v[64:65], v[70:71]
	s_nop 0
	v_pk_mov_b32 v[68:69], v[64:65], v[66:67] op_sel:[1,0]
	v_mov_b32_e32 v65, v67
	v_pk_add_f32 v[64:65], v[68:69], v[64:65]
	v_lshl_add_u64 v[66:67], v[144:145], 0, v[82:83]
	v_add_f32_e32 v64, v64, v65
	v_fmamk_f32 v64, v64, 0x3a800000, v154
	v_mul_f32_e32 v65, 0x4b800000, v64
	v_cmp_gt_f32_e32 vcc, s48, v64
	s_nop 1
	v_cndmask_b32_e32 v64, v64, v65, vcc
	v_rsq_f32_e32 v68, v64
	v_lshlrev_b64 v[64:65], 6, v[80:81]
	v_lshl_add_u64 v[64:65], s[10:11], 0, v[64:65]
	v_mul_f32_e32 v69, 0x45800000, v68
	v_cndmask_b32_e32 v68, v68, v69, vcc
	v_pk_mul_f32 v[62:63], v[62:63], v[68:69] op_sel_hi:[1,0]
	v_pk_mul_f32 v[60:61], v[60:61], v[68:69] op_sel_hi:[1,0]
	v_pk_mul_f32 v[58:59], v[58:59], v[68:69] op_sel_hi:[1,0]
	v_pk_mul_f32 v[56:57], v[56:57], v[68:69] op_sel_hi:[1,0]
	v_pk_mul_f32 v[50:51], v[50:51], v[68:69] op_sel_hi:[1,0]
	v_pk_mul_f32 v[48:49], v[48:49], v[68:69] op_sel_hi:[1,0]
	v_pk_mul_f32 v[54:55], v[54:55], v[68:69] op_sel_hi:[1,0]
	v_pk_mul_f32 v[52:53], v[52:53], v[68:69] op_sel_hi:[1,0]
	v_max_f32_e32 v60, 0, v60
	v_max_f32_e32 v56, 0, v56
	v_max_f32_e32 v61, 0, v61
	v_max_f32_e32 v57, 0, v57
	v_max_f32_e32 v62, 0, v62
	v_max_f32_e32 v58, 0, v58
	v_max_f32_e32 v63, 0, v63
	v_max_f32_e32 v59, 0, v59
	v_max_f32_e32 v48, 0, v48
	v_max_f32_e32 v49, 0, v49
	v_max_f32_e32 v50, 0, v50
	v_max_f32_e32 v51, 0, v51
	v_max_f32_e32 v52, 0, v52
	v_max_f32_e32 v53, 0, v53
	v_max_f32_e32 v54, 0, v54
	v_max_f32_e32 v55, 0, v55
	v_mul_f32_e32 v60, v60, v60
	v_mul_f32_e32 v56, v56, v56
	v_mul_f32_e32 v61, v61, v61
	v_mul_f32_e32 v57, v57, v57
	v_mul_f32_e32 v62, v62, v62
	v_mul_f32_e32 v58, v58, v58
	v_mul_f32_e32 v63, v63, v63
	v_mul_f32_e32 v59, v59, v59
	v_mul_f32_e32 v68, v48, v48
	v_mul_f32_e32 v69, v49, v49
	v_mul_f32_e32 v70, v50, v50
	v_mul_f32_e32 v71, v51, v51
	v_cvt_pk_bf16_f32 v48, v60, v61
	v_cvt_pk_bf16_f32 v49, v62, v63
	v_cvt_pk_bf16_f32 v50, v56, v57
	v_cvt_pk_bf16_f32 v51, v58, v59
	v_mul_f32_e32 v52, v52, v52
	v_mul_f32_e32 v53, v53, v53
	v_mul_f32_e32 v54, v54, v54
	v_mul_f32_e32 v55, v55, v55
	global_store_dwordx4 v[66:67], v[48:51], off sc1
	s_nop 1
	v_cvt_pk_bf16_f32 v48, v52, v53
	v_cvt_pk_bf16_f32 v49, v54, v55
	v_cvt_pk_bf16_f32 v50, v68, v69
	v_cvt_pk_bf16_f32 v51, v70, v71
	global_store_dwordx4 v[66:67], v[48:51], off offset:256 sc1
	global_load_dwordx4 v[48:51], v[64:65], off
	s_nop 0
	global_load_dwordx4 v[52:55], v[64:65], off offset:16
	global_load_dwordx4 v[56:59], v[64:65], off offset:32
	global_load_dwordx4 v[60:63], v[64:65], off offset:48
	v_add_u32_e32 v64, 0xa0, v146
	v_ashrrev_i32_e32 v65, 31, v64
	v_lshlrev_b64 v[66:67], 13, v[80:81]
	s_waitcnt vmcnt(2)
	v_pk_add_f32 v[50:51], v[50:51], v[54:55]
	v_pk_add_f32 v[48:49], v[48:49], v[52:53]
	s_waitcnt vmcnt(0)
	v_pk_add_f32 v[52:53], v[58:59], v[62:63]
	v_pk_add_f32 v[54:55], v[56:57], v[60:61]
	v_pk_add_f32 v[50:51], v[50:51], v[52:53]
	v_pk_add_f32 v[48:49], v[48:49], v[54:55]
	s_nop 0
	v_pk_mov_b32 v[52:53], v[48:49], v[50:51] op_sel:[1,0]
	v_mov_b32_e32 v49, v51
	v_pk_add_f32 v[48:49], v[52:53], v[48:49]
	v_lshl_add_u64 v[50:51], v[144:145], 0, v[66:67]
	v_add_f32_e32 v48, v48, v49
	v_fmamk_f32 v48, v48, 0x3a800000, v154
	v_mul_f32_e32 v49, 0x4b800000, v48
	v_cmp_gt_f32_e32 vcc, s48, v48
	s_nop 1
	v_cndmask_b32_e32 v48, v48, v49, vcc
	v_rsq_f32_e32 v52, v48
	v_lshlrev_b64 v[48:49], 6, v[64:65]
	v_lshl_add_u64 v[48:49], s[10:11], 0, v[48:49]
	v_mul_f32_e32 v53, 0x45800000, v52
	v_cndmask_b32_e32 v52, v52, v53, vcc
	v_pk_mul_f32 v[46:47], v[46:47], v[52:53] op_sel_hi:[1,0]
	v_pk_mul_f32 v[44:45], v[44:45], v[52:53] op_sel_hi:[1,0]
	v_pk_mul_f32 v[42:43], v[42:43], v[52:53] op_sel_hi:[1,0]
	v_pk_mul_f32 v[40:41], v[40:41], v[52:53] op_sel_hi:[1,0]
	v_pk_mul_f32 v[34:35], v[34:35], v[52:53] op_sel_hi:[1,0]
	v_pk_mul_f32 v[32:33], v[32:33], v[52:53] op_sel_hi:[1,0]
	v_pk_mul_f32 v[38:39], v[38:39], v[52:53] op_sel_hi:[1,0]
	v_pk_mul_f32 v[36:37], v[36:37], v[52:53] op_sel_hi:[1,0]
	v_max_f32_e32 v44, 0, v44
	v_max_f32_e32 v40, 0, v40
	v_max_f32_e32 v45, 0, v45
	v_max_f32_e32 v41, 0, v41
	v_max_f32_e32 v46, 0, v46
	v_max_f32_e32 v42, 0, v42
	v_max_f32_e32 v47, 0, v47
	v_max_f32_e32 v43, 0, v43
	v_max_f32_e32 v32, 0, v32
	v_max_f32_e32 v33, 0, v33
	v_max_f32_e32 v34, 0, v34
	v_max_f32_e32 v35, 0, v35
	v_max_f32_e32 v36, 0, v36
	v_max_f32_e32 v37, 0, v37
	v_max_f32_e32 v38, 0, v38
	v_max_f32_e32 v39, 0, v39
	v_mul_f32_e32 v44, v44, v44
	v_mul_f32_e32 v40, v40, v40
	v_mul_f32_e32 v45, v45, v45
	v_mul_f32_e32 v41, v41, v41
	v_mul_f32_e32 v46, v46, v46
	v_mul_f32_e32 v42, v42, v42
	v_mul_f32_e32 v47, v47, v47
	v_mul_f32_e32 v43, v43, v43
	v_mul_f32_e32 v52, v32, v32
	v_mul_f32_e32 v53, v33, v33
	v_mul_f32_e32 v54, v34, v34
	v_mul_f32_e32 v55, v35, v35
	v_cvt_pk_bf16_f32 v32, v44, v45
	v_cvt_pk_bf16_f32 v33, v46, v47
	v_cvt_pk_bf16_f32 v34, v40, v41
	v_cvt_pk_bf16_f32 v35, v42, v43
	v_mul_f32_e32 v36, v36, v36
	v_mul_f32_e32 v37, v37, v37
	v_mul_f32_e32 v38, v38, v38
	v_mul_f32_e32 v39, v39, v39
	global_store_dwordx4 v[50:51], v[32:35], off sc1
	s_nop 1
	v_cvt_pk_bf16_f32 v32, v36, v37
	v_cvt_pk_bf16_f32 v33, v38, v39
	v_cvt_pk_bf16_f32 v34, v52, v53
	v_cvt_pk_bf16_f32 v35, v54, v55
	global_store_dwordx4 v[50:51], v[32:35], off offset:256 sc1
	global_load_dwordx4 v[32:35], v[48:49], off
	s_nop 0
	global_load_dwordx4 v[36:39], v[48:49], off offset:16
	global_load_dwordx4 v[40:43], v[48:49], off offset:32
	global_load_dwordx4 v[44:47], v[48:49], off offset:48
	v_add_u32_e32 v48, 0xb0, v146
	v_ashrrev_i32_e32 v49, 31, v48
	v_lshlrev_b64 v[50:51], 13, v[64:65]
	s_waitcnt vmcnt(2)
	v_pk_add_f32 v[34:35], v[34:35], v[38:39]
	v_pk_add_f32 v[32:33], v[32:33], v[36:37]
	s_waitcnt vmcnt(0)
	v_pk_add_f32 v[36:37], v[42:43], v[46:47]
	v_pk_add_f32 v[38:39], v[40:41], v[44:45]
	v_pk_add_f32 v[34:35], v[34:35], v[36:37]
	v_pk_add_f32 v[32:33], v[32:33], v[38:39]
	s_nop 0
	v_pk_mov_b32 v[36:37], v[32:33], v[34:35] op_sel:[1,0]
	v_mov_b32_e32 v33, v35
	v_pk_add_f32 v[32:33], v[36:37], v[32:33]
	v_lshl_add_u64 v[34:35], v[144:145], 0, v[50:51]
	v_add_f32_e32 v32, v32, v33
	v_fmamk_f32 v32, v32, 0x3a800000, v154
	v_mul_f32_e32 v33, 0x4b800000, v32
	v_cmp_gt_f32_e32 vcc, s48, v32
	s_nop 1
	v_cndmask_b32_e32 v32, v32, v33, vcc
	v_rsq_f32_e32 v36, v32
	v_lshlrev_b64 v[32:33], 6, v[48:49]
	v_lshl_add_u64 v[32:33], s[10:11], 0, v[32:33]
	v_mul_f32_e32 v37, 0x45800000, v36
	v_cndmask_b32_e32 v36, v36, v37, vcc
	v_pk_mul_f32 v[30:31], v[30:31], v[36:37] op_sel_hi:[1,0]
	v_pk_mul_f32 v[28:29], v[28:29], v[36:37] op_sel_hi:[1,0]
	v_pk_mul_f32 v[26:27], v[26:27], v[36:37] op_sel_hi:[1,0]
	v_pk_mul_f32 v[24:25], v[24:25], v[36:37] op_sel_hi:[1,0]
	v_pk_mul_f32 v[18:19], v[18:19], v[36:37] op_sel_hi:[1,0]
	v_pk_mul_f32 v[16:17], v[16:17], v[36:37] op_sel_hi:[1,0]
	v_pk_mul_f32 v[22:23], v[22:23], v[36:37] op_sel_hi:[1,0]
	v_pk_mul_f32 v[20:21], v[20:21], v[36:37] op_sel_hi:[1,0]
	v_max_f32_e32 v28, 0, v28
	v_max_f32_e32 v24, 0, v24
	v_max_f32_e32 v29, 0, v29
	v_max_f32_e32 v25, 0, v25
	v_max_f32_e32 v30, 0, v30
	v_max_f32_e32 v26, 0, v26
	v_max_f32_e32 v31, 0, v31
	v_max_f32_e32 v27, 0, v27
	v_max_f32_e32 v16, 0, v16
	v_max_f32_e32 v17, 0, v17
	v_max_f32_e32 v18, 0, v18
	v_max_f32_e32 v19, 0, v19
	v_max_f32_e32 v20, 0, v20
	v_max_f32_e32 v21, 0, v21
	v_max_f32_e32 v22, 0, v22
	v_max_f32_e32 v23, 0, v23
	v_mul_f32_e32 v28, v28, v28
	v_mul_f32_e32 v24, v24, v24
	v_mul_f32_e32 v29, v29, v29
	v_mul_f32_e32 v25, v25, v25
	v_mul_f32_e32 v30, v30, v30
	v_mul_f32_e32 v26, v26, v26
	v_mul_f32_e32 v31, v31, v31
	v_mul_f32_e32 v27, v27, v27
	v_mul_f32_e32 v36, v16, v16
	v_mul_f32_e32 v37, v17, v17
	v_mul_f32_e32 v38, v18, v18
	v_mul_f32_e32 v39, v19, v19
	v_cvt_pk_bf16_f32 v16, v28, v29
	v_cvt_pk_bf16_f32 v17, v30, v31
	v_cvt_pk_bf16_f32 v18, v24, v25
	v_cvt_pk_bf16_f32 v19, v26, v27
	v_mul_f32_e32 v20, v20, v20
	v_mul_f32_e32 v21, v21, v21
	v_mul_f32_e32 v22, v22, v22
	v_mul_f32_e32 v23, v23, v23
	global_store_dwordx4 v[34:35], v[16:19], off sc1
	s_andn2_b64 vcc, exec, s[4:5]
	s_mov_b64 s[4:5], -1
	v_cvt_pk_bf16_f32 v16, v20, v21
	v_cvt_pk_bf16_f32 v17, v22, v23
	v_cvt_pk_bf16_f32 v18, v36, v37
	v_cvt_pk_bf16_f32 v19, v38, v39
	global_store_dwordx4 v[34:35], v[16:19], off offset:256 sc1
	global_load_dwordx4 v[16:19], v[32:33], off
	s_nop 0
	global_load_dwordx4 v[20:23], v[32:33], off offset:16
	global_load_dwordx4 v[24:27], v[32:33], off offset:32
	global_load_dwordx4 v[28:31], v[32:33], off offset:48
	s_waitcnt vmcnt(2)
	v_pk_add_f32 v[18:19], v[18:19], v[22:23]
	v_pk_add_f32 v[16:17], v[16:17], v[20:21]
	s_waitcnt vmcnt(0)
	v_pk_add_f32 v[20:21], v[26:27], v[30:31]
	v_pk_add_f32 v[22:23], v[24:25], v[28:29]
	v_pk_add_f32 v[18:19], v[18:19], v[20:21]
	v_pk_add_f32 v[16:17], v[16:17], v[22:23]
	s_nop 0
	v_pk_mov_b32 v[20:21], v[16:17], v[18:19] op_sel:[1,0]
	v_mov_b32_e32 v17, v19
	v_pk_add_f32 v[16:17], v[20:21], v[16:17]
	s_nop 0
	v_add_f32_e32 v16, v16, v17
	v_fmamk_f32 v16, v16, 0x3a800000, v154
	v_mul_f32_e32 v17, 0x4b800000, v16
	v_cmp_gt_f32_e64 s[6:7], s48, v16
	s_nop 1
	v_cndmask_b32_e64 v16, v16, v17, s[6:7]
	v_rsq_f32_e32 v18, v16
	v_lshlrev_b64 v[16:17], 13, v[48:49]
	v_lshl_add_u64 v[16:17], v[144:145], 0, v[16:17]
	v_mul_f32_e32 v19, 0x45800000, v18
	v_cndmask_b32_e64 v18, v18, v19, s[6:7]
	v_pk_mul_f32 v[14:15], v[14:15], v[18:19] op_sel_hi:[1,0]
	v_pk_mul_f32 v[12:13], v[12:13], v[18:19] op_sel_hi:[1,0]
	v_pk_mul_f32 v[10:11], v[10:11], v[18:19] op_sel_hi:[1,0]
	v_pk_mul_f32 v[8:9], v[8:9], v[18:19] op_sel_hi:[1,0]
	v_pk_mul_f32 v[2:3], v[2:3], v[18:19] op_sel_hi:[1,0]
	v_pk_mul_f32 v[0:1], v[0:1], v[18:19] op_sel_hi:[1,0]
	v_pk_mul_f32 v[6:7], v[6:7], v[18:19] op_sel_hi:[1,0]
	v_pk_mul_f32 v[4:5], v[4:5], v[18:19] op_sel_hi:[1,0]
	v_max_f32_e32 v12, 0, v12
	v_max_f32_e32 v8, 0, v8
	v_max_f32_e32 v13, 0, v13
	v_max_f32_e32 v9, 0, v9
	v_max_f32_e32 v14, 0, v14
	v_max_f32_e32 v10, 0, v10
	v_max_f32_e32 v15, 0, v15
	v_max_f32_e32 v11, 0, v11
	v_max_f32_e32 v0, 0, v0
	v_max_f32_e32 v1, 0, v1
	v_max_f32_e32 v2, 0, v2
	v_max_f32_e32 v3, 0, v3
	v_max_f32_e32 v4, 0, v4
	v_max_f32_e32 v5, 0, v5
	v_max_f32_e32 v6, 0, v6
	v_max_f32_e32 v7, 0, v7
	v_mul_f32_e32 v12, v12, v12
	v_mul_f32_e32 v8, v8, v8
	v_mul_f32_e32 v13, v13, v13
	v_mul_f32_e32 v9, v9, v9
	v_mul_f32_e32 v14, v14, v14
	v_mul_f32_e32 v10, v10, v10
	v_mul_f32_e32 v15, v15, v15
	v_mul_f32_e32 v11, v11, v11
	v_mul_f32_e32 v18, v0, v0
	v_mul_f32_e32 v19, v1, v1
	v_mul_f32_e32 v20, v2, v2
	v_mul_f32_e32 v21, v3, v3
	v_cvt_pk_bf16_f32 v0, v12, v13
	v_cvt_pk_bf16_f32 v1, v14, v15
	v_cvt_pk_bf16_f32 v2, v8, v9
	v_cvt_pk_bf16_f32 v3, v10, v11
	v_mul_f32_e32 v4, v4, v4
	v_mul_f32_e32 v5, v5, v5
	v_mul_f32_e32 v6, v6, v6
	v_mul_f32_e32 v7, v7, v7
	global_store_dwordx4 v[16:17], v[0:3], off sc1
	s_nop 1
	v_cvt_pk_bf16_f32 v0, v4, v5
	v_cvt_pk_bf16_f32 v1, v6, v7
	v_cvt_pk_bf16_f32 v2, v18, v19
	v_cvt_pk_bf16_f32 v3, v20, v21
	global_store_dwordx4 v[16:17], v[0:3], off offset:256 sc1
	s_cbranch_vccnz .LBB0_1357
	s_andn2_b64 vcc, exec, s[2:3]
	s_cbranch_vccnz .LBB0_1356
	s_barrier
	s_branch .LBB0_1356
